# speedup vs baseline: 1.0107x; 1.0038x over previous
; __device__ __forceinline__ void ssd_dt_acum(const float* DT, int rb, int L, int h, float a, int lane, float& dt, float& acum) {
;   dt = (lane < L) ? DT[(long)(rb + lane) * 32 + h] : 0.f;
;   float v = dt * a;
; #pragma unroll
;   for (int o = 1; o < 64; o <<= 1) { const float t = bperm(v, lane - o); if (lane >= o) v += t; }
;   acum = v;
; }
; __device__ __forceinline__ void ssd_states_item(KP P, int l, int seq, int c, int g, char* smem) {
;     ...
;   const float a = -__expf(P->a_log[l * 32 + h]);
;   float dt, acum;
;   ssd_dt_acum(DT, rb, L, h, a, lane, dt, acum);
;   const float tot = bperm(acum, 63);
;   const float scale = dt * __expf(tot - acum);
;   if (!isS && lane == 0) CD[(seq * 64 + c) * 32 + h] = __expf(tot);
; #pragma unroll
;   for (int i = 0; i < 8; ++i) {
;     const int tok = i * 8 + (lane >> 3), vec = lane & 7;
;     const float sc = bperm(scale, tok);
;     uint4 v = make_uint4(zz, zz, zz, zz);
;     if (tok < L) {
;       float f[8];
;       unpack8(*(const uint4*)(XBC + (long)(rb + tok) * 3072 + h * 64 + vec * 8), f);
; #pragma unroll
;       for (int q = 0; q < 8; ++q) f[q] *= sc;
;       v = pack8(f);
;     }
;     *(uint4*)(Xs + tok * 72 + vec * 8) = v;
.LBB0_564:
	s_or_b64 exec, exec, s[0:1]
	v_lshlrev_b32_e32 v12, 6, v0
	v_lshlrev_b32_e32 v2, 4, v16
	v_ashrrev_i32_e32 v13, 31, v12
	v_lshrrev_b32_e32 v15, 3, v14
	v_and_b32_e32 v2, 0x70, v2
	v_lshl_add_u64 v[12:13], v[12:13], 1, s[6:7]
	v_lshl_add_u64 v[12:13], v[12:13], 0, v[2:3]
	v_or_b32_e32 v17, s15, v15
	s_movk_i32 s10, 0x1800
	v_mad_u64_u32 v[18:19], s[0:1], v17, s10, v[12:13]
	s_waitcnt vmcnt(0)
	v_mul_f32_e32 v11, 0x3fb8aa3b, v11
	global_load_dwordx4 v[18:21], v[18:19], off
	v_exp_f32_e32 v11, v11
	v_lshlrev_b32_e32 v17, 2, v14
	v_add_u32_e32 v22, -4, v17
	v_or_b32_e32 v26, 8, v15
	v_mul_f32_e64 v23, v10, -v11
	ds_bpermute_b32 v22, v22, v23
	v_cmp_eq_u32_e32 vcc, 0, v14
	v_or_b32_e32 v25, s15, v26
	v_add_u32_e32 v24, -8, v17
	v_mad_u64_u32 v[12:13], s[0:1], v25, s10, v[12:13]
	s_waitcnt lgkmcnt(0)
	v_fma_f32 v11, v10, -v11, v22
	v_cndmask_b32_e32 v11, v11, v23, vcc
	ds_bpermute_b32 v27, v24, v11
	global_load_dwordx4 v[22:25], v[12:13], off
	v_cmp_gt_u32_e64 s[6:7], 2, v14
	v_add_u32_e32 v12, -16, v17
	v_cmp_gt_u32_e32 vcc, 4, v14
	s_waitcnt lgkmcnt(0)
	v_add_f32_e32 v13, v11, v27
	v_cndmask_b32_e64 v11, v13, v11, s[6:7]
	ds_bpermute_b32 v12, v12, v11
	v_subrev_u32_e32 v13, 32, v17
	s_movk_i32 s0, 0x2400
	v_mul_lo_u32 v9, v9, s0
	s_add_i32 s26, s18, s60
	s_waitcnt lgkmcnt(0)
	v_add_f32_e32 v12, v11, v12
	v_cndmask_b32_e32 v11, v12, v11, vcc
	ds_bpermute_b32 v12, v13, v11
	v_cmp_gt_u32_e32 vcc, 8, v14
	v_subrev_u32_e32 v13, 64, v17
	s_lshl_b64 s[6:7], s[26:27], 18
	v_lshlrev_b64 v[0:1], 13, v[0:1]
	s_waitcnt lgkmcnt(0)
	v_add_f32_e32 v12, v11, v12
	v_cndmask_b32_e32 v11, v12, v11, vcc
	ds_bpermute_b32 v12, v13, v11
	v_add_u32_e32 v13, 0xffffff80, v17
	v_cmp_gt_u32_e32 vcc, 32, v14
	v_add_u32_e32 v17, 0, v9
	v_lshl_add_u64 v[0:1], v[0:1], 0, s[6:7]
	s_waitcnt lgkmcnt(0)
	v_add_f32_e32 v12, v11, v12
	v_cndmask_b32_e64 v11, v12, v11, s[4:5]
	ds_bpermute_b32 v12, v13, v11
	v_or_b32_e32 v91, 16, v85
	v_or_b32_e32 v92, 32, v85
	v_or_b32_e32 v94, 48, v85
	v_or_b32_e32 v93, 64, v85
	s_waitcnt lgkmcnt(0)
	v_add_f32_e32 v9, v11, v12
	v_cndmask_b32_e32 v9, v9, v11, vcc
	v_lshlrev_b32_e32 v11, 2, v15
	v_readlane_b32 s0, v9, 63
	v_mul_u32_u24_e32 v12, 0x90, v15
	v_add3_u32 v15, v17, v2, v12
	v_sub_f32_e32 v9, s0, v9
	v_mul_f32_e32 v9, 0x3fb8aa3b, v9
	v_exp_f32_e32 v9, v9
	v_or_b32_e32 v90, 0x50, v85
	v_or_b32_e32 v89, 0x60, v85
	v_readlane_b32 s6, v252, 3
	v_mul_f32_e32 v9, v10, v9
	ds_bpermute_b32 v2, v11, v9
	v_readlane_b32 s7, v252, 4
	s_movk_i32 s19, 0x1800
	s_waitcnt vmcnt(1)
	v_and_b32_e32 v11, 0xffff0000, v19
	v_and_b32_e32 v10, 0xffff0000, v18
	v_lshlrev_b32_e32 v13, 16, v19
	v_lshlrev_b32_e32 v12, 16, v18
	v_and_b32_e32 v19, 0xffff0000, v21
	v_and_b32_e32 v18, 0xffff0000, v20
	v_lshlrev_b32_e32 v21, 16, v21
	v_lshlrev_b32_e32 v20, 16, v20
	s_waitcnt lgkmcnt(0)
	v_pk_mul_f32 v[10:11], v[2:3], v[10:11] op_sel_hi:[0,1]
	v_pk_mul_f32 v[12:13], v[2:3], v[12:13] op_sel_hi:[0,1]
	v_pk_mul_f32 v[18:19], v[2:3], v[18:19] op_sel_hi:[0,1]
	v_pk_mul_f32 v[20:21], v[2:3], v[20:21] op_sel_hi:[0,1]
	v_and_b32_sdwa v2, v11, v226 dst_sel:DWORD dst_unused:UNUSED_PAD src0_sel:WORD_1 src1_sel:DWORD
	v_and_b32_sdwa v27, v10, v226 dst_sel:DWORD dst_unused:UNUSED_PAD src0_sel:WORD_1 src1_sel:DWORD
	v_and_b32_sdwa v28, v13, v226 dst_sel:DWORD dst_unused:UNUSED_PAD src0_sel:WORD_1 src1_sel:DWORD
	v_add3_u32 v2, v11, v2, s33
	v_and_b32_sdwa v29, v12, v226 dst_sel:DWORD dst_unused:UNUSED_PAD src0_sel:WORD_1 src1_sel:DWORD
	v_and_b32_sdwa v30, v19, v226 dst_sel:DWORD dst_unused:UNUSED_PAD src0_sel:WORD_1 src1_sel:DWORD
	v_add3_u32 v10, v10, v27, s33
	v_add3_u32 v11, v13, v28, s33
	v_and_b32_e32 v2, 0xffff0000, v2
	v_and_b32_sdwa v32, v21, v226 dst_sel:DWORD dst_unused:UNUSED_PAD src0_sel:WORD_1 src1_sel:DWORD
	v_add3_u32 v12, v12, v29, s33
	v_add3_u32 v13, v19, v30, s33
	v_and_b32_e32 v10, 0xffff0000, v10
	v_or_b32_sdwa v11, v2, v11 dst_sel:DWORD dst_unused:UNUSED_PAD src0_sel:DWORD src1_sel:WORD_1
	v_and_b32_sdwa v2, v20, v226 dst_sel:DWORD dst_unused:UNUSED_PAD src0_sel:WORD_1 src1_sel:DWORD
	v_and_b32_e32 v13, 0xffff0000, v13
	v_or_b32_sdwa v10, v10, v12 dst_sel:DWORD dst_unused:UNUSED_PAD src0_sel:DWORD src1_sel:WORD_1
	v_add3_u32 v12, v20, v2, s33
	v_add3_u32 v2, v21, v32, s33
	v_or_b32_sdwa v13, v13, v2 dst_sel:DWORD dst_unused:UNUSED_PAD src0_sel:DWORD src1_sel:WORD_1
	v_lshlrev_b32_e32 v2, 2, v26
	v_and_b32_sdwa v31, v18, v226 dst_sel:DWORD dst_unused:UNUSED_PAD src0_sel:WORD_1 src1_sel:DWORD
	ds_bpermute_b32 v2, v2, v9
	v_add3_u32 v18, v18, v31, s33
	v_and_b32_e32 v18, 0xffff0000, v18
	v_or_b32_sdwa v12, v18, v12 dst_sel:DWORD dst_unused:UNUSED_PAD src0_sel:DWORD src1_sel:WORD_1
	ds_write_b128 v15, v[10:13] offset:17408
	s_waitcnt vmcnt(0)
	v_and_b32_e32 v11, 0xffff0000, v23
	v_and_b32_e32 v10, 0xffff0000, v22
	s_waitcnt lgkmcnt(1)
; __device__ __forceinline__ bf16x8 cat44(s16x4 a, s16x4 b) { return (bf16x8){a[0], a[1], a[2], a[3], b[0], b[1], b[2], b[3]}; }
; __device__ __forceinline__ void ssd_states_item(KP P, int l, int seq, int c, int g, char* smem) {
;     ...
;   __syncthreads();
;   f32x4 acc[4][8] = {};
;   const int trr = (lane >> 4) * 8 + ((lane >> 2) & 3), trc = (lane & 3) * 4;
; #pragma unroll
;   for (int ks = 0; ks < 2; ++ks) {
;     bf16x8 af[4];
; #pragma unroll
;     for (int mb = 0; mb < 4; ++mb) {
;       const u16* p0 = Xs + (ks * 32 + trr) * 72 + mb * 16 + trc;
;       af[mb] = cat44(ldtr(p0), ldtr(p0 + 4 * 72));
;     }
; #pragma unroll
;     for (int nb = 0; nb < 8; ++nb) {
;       const u16* p0 = Bs + (ks * 32 + trr) * 136 + nb * 16 + trc;
;       const bf16x8 bf = cat44(ldtr(p0), ldtr(p0 + 4 * 136));
; #pragma unroll
;       for (int mb = 0; mb < 4; ++mb) acc[mb][nb] = __builtin_amdgcn_mfma_f32_16x16x32_bf16(af[mb], bf, acc[mb][nb], 0, 0, 0);
;     }
;   }
;   if (!isS) {
;     u16* dst = (u16*)ST + ((long)(seq * 64 + c) * 32 + h) * 8192;
; #pragma unroll
;     for (int mb = 0; mb < 4; ++mb)
; #pragma unroll
;       for (int nb = 0; nb < 8; ++nb)
; #pragma unroll
;         for (int j = 0; j < 4; ++j) dst[(mb * 16 + (lane >> 4) * 4 + j) * 128 + nb * 16 + (lane & 15)] = f2bf(acc[mb][nb][j]);
;   } else {
;     const int bs = seq - 2;
;     const float* h0 = P->st_ssm + ((long)(l * 8 + bs) * 32 + h) * 8192;
;     float* dst = P->out + O_SSMS + ((long)(l * 8 + bs) * 32 + h) * 8192;
;     const float bd = __expf(tot);
; #pragma unroll
;     for (int mb = 0; mb < 4; ++mb)
; #pragma unroll
;       for (int nb = 0; nb < 8; ++nb)
; #pragma unroll
;         for (int j = 0; j < 4; ++j) {
;           const int o = (mb * 16 + (lane >> 4) * 4 + j) * 128 + nb * 16 + (lane & 15);
;           dst[o] = h0[o] * bd + acc[mb][nb][j];
;         }
	v_pk_mul_f32 v[10:11], v[2:3], v[10:11] op_sel_hi:[0,1]
	v_lshlrev_b32_e32 v13, 16, v23
	v_lshlrev_b32_e32 v12, 16, v22
	v_pk_mul_f32 v[12:13], v[2:3], v[12:13] op_sel_hi:[0,1]
	v_and_b32_sdwa v18, v10, v226 dst_sel:DWORD dst_unused:UNUSED_PAD src0_sel:WORD_1 src1_sel:DWORD
	v_and_b32_sdwa v9, v11, v226 dst_sel:DWORD dst_unused:UNUSED_PAD src0_sel:WORD_1 src1_sel:DWORD
	v_add3_u32 v10, v10, v18, s33
	v_and_b32_sdwa v18, v12, v226 dst_sel:DWORD dst_unused:UNUSED_PAD src0_sel:WORD_1 src1_sel:DWORD
	v_add3_u32 v9, v11, v9, s33
	v_and_b32_e32 v10, 0xffff0000, v10
	v_and_b32_sdwa v11, v13, v226 dst_sel:DWORD dst_unused:UNUSED_PAD src0_sel:WORD_1 src1_sel:DWORD
	v_add3_u32 v12, v12, v18, s33
	v_add3_u32 v11, v13, v11, s33
	v_or_b32_sdwa v10, v10, v12 dst_sel:DWORD dst_unused:UNUSED_PAD src0_sel:DWORD src1_sel:WORD_1
	v_and_b32_e32 v13, 0xffff0000, v25
	v_and_b32_e32 v12, 0xffff0000, v24
	v_and_b32_e32 v9, 0xffff0000, v9
	v_pk_mul_f32 v[12:13], v[2:3], v[12:13] op_sel_hi:[0,1]
	v_lshlrev_b32_e32 v19, 16, v25
	v_lshlrev_b32_e32 v18, 16, v24
	v_or_b32_sdwa v11, v9, v11 dst_sel:DWORD dst_unused:UNUSED_PAD src0_sel:DWORD src1_sel:WORD_1
	v_pk_mul_f32 v[18:19], v[2:3], v[18:19] op_sel_hi:[0,1]
	v_and_b32_sdwa v2, v13, v226 dst_sel:DWORD dst_unused:UNUSED_PAD src0_sel:WORD_1 src1_sel:DWORD
	v_and_b32_sdwa v9, v12, v226 dst_sel:DWORD dst_unused:UNUSED_PAD src0_sel:WORD_1 src1_sel:DWORD
	v_add3_u32 v2, v13, v2, s33
	v_add3_u32 v9, v12, v9, s33
	v_and_b32_sdwa v12, v19, v226 dst_sel:DWORD dst_unused:UNUSED_PAD src0_sel:WORD_1 src1_sel:DWORD
	v_and_b32_sdwa v13, v18, v226 dst_sel:DWORD dst_unused:UNUSED_PAD src0_sel:WORD_1 src1_sel:DWORD
	v_and_b32_e32 v2, 0xffff0000, v2
	v_and_b32_e32 v9, 0xffff0000, v9
	v_add3_u32 v18, v18, v13, s33
	v_add3_u32 v12, v19, v12, s33
	v_or_b32_sdwa v13, v2, v12 dst_sel:DWORD dst_unused:UNUSED_PAD src0_sel:DWORD src1_sel:WORD_1
	v_or_b32_sdwa v12, v9, v18 dst_sel:DWORD dst_unused:UNUSED_PAD src0_sel:DWORD src1_sel:WORD_1
	ds_write_b128 v15, v[10:13] offset:18560
	v_mov_b32_e32 v9, v8
	v_mov_b32_e32 v10, v8
	v_mov_b32_e32 v11, v8
	ds_write_b128 v15, v[8:11] offset:19712
	ds_write_b128 v15, v[8:11] offset:20864
	ds_write_b128 v15, v[8:11] offset:22016
	ds_write_b128 v15, v[8:11] offset:23168
	ds_write_b128 v15, v[8:11] offset:24320
	ds_write_b128 v15, v[8:11] offset:25472
	s_waitcnt lgkmcnt(0)
	s_barrier
	s_load_dwordx2 s[4:5], s[8:9], 0x20
	v_lshrrev_b32_e32 v8, 4, v14
	v_lshlrev_b32_e32 v87, 9, v8
	v_lshlrev_b64 v[18:19], 2, v[0:1]
	v_or_b32_e32 v2, v87, v85
	s_waitcnt lgkmcnt(0)
	v_lshl_add_u64 v[0:1], s[4:5], 0, v[18:19]
	v_and_b32_e32 v216, 63, v188
	v_lshlrev_b32_e32 v216, 9, v216
	v_mov_b32_e32 v217, 0
	v_lshl_add_u64 v[218:219], v[0:1], 0, v[216:217]
	global_load_dword v220, v[218:219], off
	global_load_dword v220, v[218:219], off offset:128
	global_load_dword v220, v[218:219], off offset:256
	global_load_dword v220, v[218:219], off offset:384
	v_lshlrev_b32_e32 v2, 2, v2
	v_lshl_add_u64 v[12:13], v[0:1], 0, v[2:3]
	global_load_dword v20, v[12:13], off
	v_bfe_u32 v9, v16, 2, 2
	v_lshl_or_b32 v8, v8, 3, v9
	v_lshlrev_b32_e32 v9, 3, v16
	v_and_b32_e32 v9, 24, v9
	v_mul_u32_u24_e32 v10, 0x90, v8
	v_add3_u32 v95, v17, v9, v10
	ds_read_b64_tr_b16 v[72:73], v95 offset:17408
	ds_read_b64_tr_b16 v[74:75], v95 offset:17984
	v_mul_u32_u24_e32 v8, 0x110, v8
	v_add3_u32 v88, 0, v9, v8
	ds_read_b64_tr_b16 v[70:71], v88 offset:1088
	ds_read_b64_tr_b16 v[68:69], v88
	ds_read_b64_tr_b16 v[76:77], v95 offset:22016
	ds_read_b64_tr_b16 v[78:79], v95 offset:22592
	ds_read_b64_tr_b16 v[8:9], v88 offset:8704
	ds_read_b64_tr_b16 v[10:11], v88 offset:9792
	s_waitcnt lgkmcnt(4)
	v_mfma_f32_16x16x32_bf16 v[14:17], v[72:75], v[68:71], 0
	s_load_dwordx2 s[4:5], s[8:9], 0xd0
	v_mul_f32_e32 v21, s0, v233
	v_exp_f32_e32 v86, v21
	s_waitcnt lgkmcnt(0)
	v_mfma_f32_16x16x32_bf16 v[14:17], v[76:79], v[8:11], v[14:17]
	s_mov_b64 s[0:1], 0x6900000
	v_lshl_add_u64 v[18:19], s[4:5], 0, v[18:19]
	v_lshl_add_u64 v[80:81], v[18:19], 0, s[0:1]
	v_lshl_add_u64 v[82:83], v[80:81], 0, v[2:3]
	v_or_b32_e32 v104, 0x800, v87
	v_or_b32_e32 v105, 0x880, v87
	v_or_b32_e32 v100, v105, v85
	v_or_b32_e32 v106, 0x900, v87
	v_or_b32_e32 v107, 0x980, v87
	v_or_b32_e32 v109, v105, v91
	v_or_b32_e32 v110, 0x1180, v87
	s_mov_b64 s[0:1], 0
	global_load_dword v208, v[12:13], off offset:512
	global_load_dword v209, v[12:13], off offset:1024
	global_load_dword v210, v[12:13], off offset:1536
	s_waitcnt vmcnt(0)
	v_fma_f32 v14, v86, v20, v14
	global_store_dword v[82:83], v14, off
	v_mov_b32_e32 v2, v208
	v_fma_f32 v2, v86, v2, v15
	global_store_dword v[82:83], v2, off offset:512
	v_mov_b32_e32 v2, v209
	v_fma_f32 v2, v86, v2, v16
	global_store_dword v[82:83], v2, off offset:1024
	v_mov_b32_e32 v2, v210
	v_fmac_f32_e32 v17, v86, v2
	global_store_dword v[82:83], v17, off offset:1536
	global_load_dword v20, v[12:13], off offset:64
	ds_read_b64_tr_b16 v[40:41], v88 offset:32
	ds_read_b64_tr_b16 v[42:43], v88 offset:1120
	ds_read_b64_tr_b16 v[32:33], v88 offset:8736
	ds_read_b64_tr_b16 v[34:35], v88 offset:9824
	s_waitcnt lgkmcnt(2)
	v_mfma_f32_16x16x32_bf16 v[14:17], v[72:75], v[40:43], 0
	v_or_b32_e32 v2, v87, v91
	v_lshlrev_b32_e32 v2, 2, v2
	v_lshl_add_u64 v[18:19], v[0:1], 0, v[2:3]
	s_waitcnt lgkmcnt(0)
	v_mfma_f32_16x16x32_bf16 v[14:17], v[76:79], v[32:35], v[14:17]
	global_load_dword v208, v[18:19], off offset:512
	global_load_dword v209, v[18:19], off offset:1024
	global_load_dword v210, v[18:19], off offset:1536
	s_waitcnt vmcnt(0)
; __device__ __forceinline__ void ssd_states_item(KP P, int l, int seq, int c, int g, char* smem) {
;     ...
;   } else {
;     const int bs = seq - 2;
;     const float* h0 = P->st_ssm + ((long)(l * 8 + bs) * 32 + h) * 8192;
;     float* dst = P->out + O_SSMS + ((long)(l * 8 + bs) * 32 + h) * 8192;
;     const float bd = __expf(tot);
; #pragma unroll
;     for (int mb = 0; mb < 4; ++mb)
; #pragma unroll
;       for (int nb = 0; nb < 8; ++nb)
; #pragma unroll
;         for (int j = 0; j < 4; ++j) {
;           const int o = (mb * 16 + (lane >> 4) * 4 + j) * 128 + nb * 16 + (lane & 15);
;           dst[o] = h0[o] * bd + acc[mb][nb][j];
;         }
	s_nop 6
	v_fma_f32 v14, v86, v20, v14
	global_store_dword v[82:83], v14, off offset:64
	v_mov_b32_e32 v14, v208
	v_lshl_add_u64 v[20:21], v[80:81], 0, v[2:3]
	v_fma_f32 v2, v86, v14, v15
	global_store_dword v[20:21], v2, off offset:512
	v_mov_b32_e32 v2, v209
	v_fma_f32 v2, v86, v2, v16
	global_store_dword v[20:21], v2, off offset:1024
	v_mov_b32_e32 v2, v210
	v_fmac_f32_e32 v17, v86, v2
	global_store_dword v[20:21], v17, off offset:1536
	global_load_dword v20, v[12:13], off offset:128
	ds_read_b64_tr_b16 v[52:53], v88 offset:64
	ds_read_b64_tr_b16 v[54:55], v88 offset:1152
	ds_read_b64_tr_b16 v[44:45], v88 offset:8768
	ds_read_b64_tr_b16 v[46:47], v88 offset:9856
	s_waitcnt lgkmcnt(2)
	v_mfma_f32_16x16x32_bf16 v[14:17], v[72:75], v[52:55], 0
	v_or_b32_e32 v2, v87, v92
	v_lshlrev_b32_e32 v2, 2, v2
	v_lshl_add_u64 v[18:19], v[0:1], 0, v[2:3]
	s_waitcnt lgkmcnt(0)
	v_mfma_f32_16x16x32_bf16 v[14:17], v[76:79], v[44:47], v[14:17]
	global_load_dword v208, v[18:19], off offset:512
	global_load_dword v209, v[18:19], off offset:1024
	global_load_dword v210, v[18:19], off offset:1536
	s_waitcnt vmcnt(0)
	s_nop 6
	v_fma_f32 v14, v86, v20, v14
	global_store_dword v[82:83], v14, off offset:128
	v_mov_b32_e32 v14, v208
	v_lshl_add_u64 v[20:21], v[80:81], 0, v[2:3]
	v_fma_f32 v2, v86, v14, v15
	global_store_dword v[20:21], v2, off offset:512
	v_mov_b32_e32 v2, v209
	v_fma_f32 v2, v86, v2, v16
	global_store_dword v[20:21], v2, off offset:1024
	v_mov_b32_e32 v2, v210
	v_fmac_f32_e32 v17, v86, v2
	global_store_dword v[20:21], v17, off offset:1536
	global_load_dword v20, v[12:13], off offset:192
	ds_read_b64_tr_b16 v[64:65], v88 offset:96
	ds_read_b64_tr_b16 v[66:67], v88 offset:1184
	ds_read_b64_tr_b16 v[60:61], v88 offset:8800
	ds_read_b64_tr_b16 v[62:63], v88 offset:9888
	s_waitcnt lgkmcnt(2)
	v_mfma_f32_16x16x32_bf16 v[14:17], v[72:75], v[64:67], 0
	v_or_b32_e32 v2, v87, v94
	v_lshlrev_b32_e32 v2, 2, v2
	v_lshl_add_u64 v[18:19], v[0:1], 0, v[2:3]
	s_waitcnt lgkmcnt(0)
	v_mfma_f32_16x16x32_bf16 v[14:17], v[76:79], v[60:63], v[14:17]
	global_load_dword v208, v[18:19], off offset:512
	global_load_dword v209, v[18:19], off offset:1024
	global_load_dword v210, v[18:19], off offset:1536
	s_waitcnt vmcnt(0)
	s_nop 6
	v_fma_f32 v14, v86, v20, v14
	global_store_dword v[82:83], v14, off offset:192
	v_mov_b32_e32 v14, v208
	v_lshl_add_u64 v[20:21], v[80:81], 0, v[2:3]
	v_fma_f32 v2, v86, v14, v15
	global_store_dword v[20:21], v2, off offset:512
	v_mov_b32_e32 v2, v209
	v_fma_f32 v2, v86, v2, v16
	global_store_dword v[20:21], v2, off offset:1024
	v_mov_b32_e32 v2, v210
	v_fmac_f32_e32 v17, v86, v2
	global_store_dword v[20:21], v17, off offset:1536
	global_load_dword v20, v[12:13], off offset:256
	ds_read_b64_tr_b16 v[56:57], v88 offset:128
	ds_read_b64_tr_b16 v[58:59], v88 offset:1216
	ds_read_b64_tr_b16 v[48:49], v88 offset:8832
	ds_read_b64_tr_b16 v[50:51], v88 offset:9920
	s_waitcnt lgkmcnt(2)
	v_mfma_f32_16x16x32_bf16 v[14:17], v[72:75], v[56:59], 0
	v_or_b32_e32 v2, v87, v93
	v_lshlrev_b32_e32 v2, 2, v2
	v_lshl_add_u64 v[18:19], v[0:1], 0, v[2:3]
	s_waitcnt lgkmcnt(0)
	v_mfma_f32_16x16x32_bf16 v[14:17], v[76:79], v[48:51], v[14:17]
	global_load_dword v208, v[18:19], off offset:512
	global_load_dword v209, v[18:19], off offset:1024
	global_load_dword v210, v[18:19], off offset:1536
	s_waitcnt vmcnt(0)
	s_nop 6
	v_fma_f32 v14, v86, v20, v14
	global_store_dword v[82:83], v14, off offset:256
	v_mov_b32_e32 v14, v208
	v_lshl_add_u64 v[20:21], v[80:81], 0, v[2:3]
	v_fma_f32 v2, v86, v14, v15
	global_store_dword v[20:21], v2, off offset:512
	v_mov_b32_e32 v2, v209
	v_fma_f32 v2, v86, v2, v16
	global_store_dword v[20:21], v2, off offset:1024
	v_mov_b32_e32 v2, v210
	v_fmac_f32_e32 v17, v86, v2
	global_store_dword v[20:21], v17, off offset:1536
	global_load_dword v20, v[12:13], off offset:320
	ds_read_b64_tr_b16 v[36:37], v88 offset:160
	ds_read_b64_tr_b16 v[38:39], v88 offset:1248
	ds_read_b64_tr_b16 v[28:29], v88 offset:8864
	ds_read_b64_tr_b16 v[30:31], v88 offset:9952
	s_waitcnt lgkmcnt(2)
	v_mfma_f32_16x16x32_bf16 v[14:17], v[72:75], v[36:39], 0
	v_or_b32_e32 v2, v87, v90
	v_lshlrev_b32_e32 v2, 2, v2
	v_lshl_add_u64 v[18:19], v[0:1], 0, v[2:3]
	s_waitcnt lgkmcnt(0)
	v_mfma_f32_16x16x32_bf16 v[14:17], v[76:79], v[28:31], v[14:17]
	global_load_dword v208, v[18:19], off offset:512
	global_load_dword v209, v[18:19], off offset:1024
	global_load_dword v210, v[18:19], off offset:1536
	s_waitcnt vmcnt(0)
	s_nop 6
	v_fma_f32 v14, v86, v20, v14
	global_store_dword v[82:83], v14, off offset:320
	v_mov_b32_e32 v14, v208
	v_lshl_add_u64 v[20:21], v[80:81], 0, v[2:3]
	v_fma_f32 v2, v86, v14, v15
	global_store_dword v[20:21], v2, off offset:512
	v_mov_b32_e32 v2, v209
	v_fma_f32 v2, v86, v2, v16
	global_store_dword v[20:21], v2, off offset:1024
	v_mov_b32_e32 v2, v210
	v_fmac_f32_e32 v17, v86, v2
	global_store_dword v[20:21], v17, off offset:1536
	global_load_dword v96, v[12:13], off offset:384
	ds_read_b64_tr_b16 v[24:25], v88 offset:192
	ds_read_b64_tr_b16 v[26:27], v88 offset:1280
	ds_read_b64_tr_b16 v[20:21], v88 offset:8896
	ds_read_b64_tr_b16 v[22:23], v88 offset:9984
	s_waitcnt lgkmcnt(2)
	v_mfma_f32_16x16x32_bf16 v[14:17], v[72:75], v[24:27], 0
	v_or_b32_e32 v2, v87, v89
	v_lshlrev_b32_e32 v2, 2, v2
	v_lshl_add_u64 v[18:19], v[0:1], 0, v[2:3]
	s_waitcnt lgkmcnt(0)
	v_mfma_f32_16x16x32_bf16 v[14:17], v[76:79], v[20:23], v[14:17]
	global_load_dword v208, v[18:19], off offset:512
	global_load_dword v209, v[18:19], off offset:1024
	global_load_dword v210, v[18:19], off offset:1536
	s_waitcnt vmcnt(0)
; __device__ __forceinline__ void ssd_states_item(KP P, int l, int seq, int c, int g, char* smem) {
;     ...
;   } else {
;     const int bs = seq - 2;
;     const float* h0 = P->st_ssm + ((long)(l * 8 + bs) * 32 + h) * 8192;
;     float* dst = P->out + O_SSMS + ((long)(l * 8 + bs) * 32 + h) * 8192;
;     const float bd = __expf(tot);
; #pragma unroll
;     for (int mb = 0; mb < 4; ++mb)
; #pragma unroll
;       for (int nb = 0; nb < 8; ++nb)
; #pragma unroll
;         for (int j = 0; j < 4; ++j) {
;           const int o = (mb * 16 + (lane >> 4) * 4 + j) * 128 + nb * 16 + (lane & 15);
;           dst[o] = h0[o] * bd + acc[mb][nb][j];
;         }
	s_nop 6
	v_fma_f32 v14, v86, v96, v14
	global_store_dword v[82:83], v14, off offset:384
	v_mov_b32_e32 v14, v208
	v_lshl_add_u64 v[96:97], v[80:81], 0, v[2:3]
	v_fma_f32 v2, v86, v14, v15
	global_store_dword v[96:97], v2, off offset:512
	v_mov_b32_e32 v2, v209
	v_fma_f32 v2, v86, v2, v16
	global_store_dword v[96:97], v2, off offset:1024
	v_mov_b32_e32 v2, v210
	v_fmac_f32_e32 v17, v86, v2
	global_store_dword v[96:97], v17, off offset:1536
	global_load_dword v96, v[12:13], off offset:448
	ds_read_b64_tr_b16 v[16:17], v88 offset:224
	ds_read_b64_tr_b16 v[18:19], v88 offset:1312
	ds_read_b64_tr_b16 v[12:13], v88 offset:8928
	ds_read_b64_tr_b16 v[14:15], v88 offset:10016
	s_waitcnt lgkmcnt(2)
	v_mfma_f32_16x16x32_bf16 v[72:75], v[72:75], v[16:19], 0
	v_or_b32_e32 v88, 0x70, v85
	v_or_b32_e32 v2, v87, v88
	v_lshlrev_b32_e32 v2, 2, v2
	s_waitcnt lgkmcnt(0)
	v_mfma_f32_16x16x32_bf16 v[72:75], v[76:79], v[12:15], v[72:75]
	v_lshl_add_u64 v[76:77], v[0:1], 0, v[2:3]
	v_lshl_add_u64 v[78:79], v[80:81], 0, v[2:3]
	s_waitcnt vmcnt(0)
	s_nop 4
	v_fma_f32 v72, v86, v96, v72
	global_load_dword v72, v[76:77], off offset:512
	global_store_dword v[82:83], v72, off offset:448
	s_waitcnt vmcnt(1)
	v_fma_f32 v2, v86, v72, v73
	global_load_dword v2, v[76:77], off offset:1024
	global_store_dword v[78:79], v2, off offset:512
	s_waitcnt vmcnt(1)
	v_fma_f32 v2, v86, v2, v74
	global_load_dword v74, v[76:77], off offset:1536
	global_store_dword v[78:79], v2, off offset:1024
	v_or_b32_e32 v2, v104, v85
	v_lshlrev_b32_e32 v2, 2, v2
	v_lshl_add_u64 v[72:73], v[0:1], 0, v[2:3]
	v_lshl_add_u64 v[82:83], v[80:81], 0, v[2:3]
	v_lshlrev_b32_e32 v2, 2, v100
	v_lshl_add_u64 v[100:101], v[0:1], 0, v[2:3]
	s_waitcnt vmcnt(1)
	v_fmac_f32_e32 v75, v86, v74
	global_load_dword v102, v[72:73], off
	global_store_dword v[78:79], v75, off offset:1536
	ds_read_b64_tr_b16 v[72:73], v95 offset:17440
	ds_read_b64_tr_b16 v[74:75], v95 offset:18016
	ds_read_b64_tr_b16 v[76:77], v95 offset:22048
	ds_read_b64_tr_b16 v[78:79], v95 offset:22624
	s_waitcnt lgkmcnt(2)
	v_mfma_f32_16x16x32_bf16 v[96:99], v[72:75], v[68:71], 0
	s_waitcnt lgkmcnt(0)
	v_mfma_f32_16x16x32_bf16 v[96:99], v[76:79], v[8:11], v[96:99]
	s_waitcnt vmcnt(1)
	s_nop 6
	v_fma_f32 v96, v86, v102, v96
	global_load_dword v96, v[100:101], off
	global_store_dword v[82:83], v96, off
	v_or_b32_e32 v100, v106, v85
	v_lshl_add_u64 v[82:83], v[80:81], 0, v[2:3]
	v_lshlrev_b32_e32 v2, 2, v100
	v_lshl_add_u64 v[100:101], v[0:1], 0, v[2:3]
	s_waitcnt vmcnt(1)
	v_fma_f32 v96, v86, v96, v97
	global_load_dword v100, v[100:101], off
	global_store_dword v[82:83], v96, off
	v_or_b32_e32 v96, v107, v85
	v_lshl_add_u64 v[82:83], v[80:81], 0, v[2:3]
	v_lshlrev_b32_e32 v2, 2, v96
	v_lshl_add_u64 v[96:97], v[0:1], 0, v[2:3]
	s_waitcnt vmcnt(1)
	v_fma_f32 v98, v86, v100, v98
	global_load_dword v98, v[96:97], off
	global_store_dword v[82:83], v98, off
	v_or_b32_e32 v96, v104, v91
	v_lshl_add_u64 v[82:83], v[80:81], 0, v[2:3]
	v_lshlrev_b32_e32 v2, 2, v96
	v_lshl_add_u64 v[96:97], v[0:1], 0, v[2:3]
	v_mfma_f32_16x16x32_bf16 v[100:103], v[72:75], v[40:43], 0
	s_waitcnt vmcnt(1)
	v_fmac_f32_e32 v99, v86, v98
	global_load_dword v108, v[96:97], off
	global_store_dword v[82:83], v99, off
	v_mfma_f32_16x16x32_bf16 v[96:99], v[76:79], v[32:35], v[100:103]
	v_lshl_add_u64 v[82:83], v[80:81], 0, v[2:3]
	v_lshlrev_b32_e32 v2, 2, v109
	v_or_b32_e32 v109, v105, v92
	v_lshl_add_u64 v[100:101], v[0:1], 0, v[2:3]
	s_waitcnt vmcnt(1)
	s_nop 2
	v_fma_f32 v96, v86, v108, v96
	global_load_dword v96, v[100:101], off
	global_store_dword v[82:83], v96, off
	v_or_b32_e32 v100, v106, v91
	v_lshl_add_u64 v[82:83], v[80:81], 0, v[2:3]
	v_lshlrev_b32_e32 v2, 2, v100
	v_lshl_add_u64 v[100:101], v[0:1], 0, v[2:3]
	s_waitcnt vmcnt(1)
	v_fma_f32 v96, v86, v96, v97
	global_load_dword v100, v[100:101], off
	global_store_dword v[82:83], v96, off
	v_or_b32_e32 v96, v107, v91
	v_lshl_add_u64 v[82:83], v[80:81], 0, v[2:3]
	v_lshlrev_b32_e32 v2, 2, v96
	v_lshl_add_u64 v[96:97], v[0:1], 0, v[2:3]
	s_waitcnt vmcnt(1)
	v_fma_f32 v98, v86, v100, v98
	global_load_dword v98, v[96:97], off
	global_store_dword v[82:83], v98, off
	v_or_b32_e32 v96, v104, v92
	v_lshl_add_u64 v[82:83], v[80:81], 0, v[2:3]
	v_lshlrev_b32_e32 v2, 2, v96
	v_lshl_add_u64 v[96:97], v[0:1], 0, v[2:3]
	v_mfma_f32_16x16x32_bf16 v[100:103], v[72:75], v[52:55], 0
	s_waitcnt vmcnt(1)
	v_fmac_f32_e32 v99, v86, v98
	global_load_dword v108, v[96:97], off
	global_store_dword v[82:83], v99, off
	v_mfma_f32_16x16x32_bf16 v[96:99], v[76:79], v[44:47], v[100:103]
	v_lshl_add_u64 v[82:83], v[80:81], 0, v[2:3]
	v_lshlrev_b32_e32 v2, 2, v109
	v_or_b32_e32 v109, v105, v94
	v_lshl_add_u64 v[100:101], v[0:1], 0, v[2:3]
	s_waitcnt vmcnt(1)
	s_nop 2
	v_fma_f32 v96, v86, v108, v96
	global_load_dword v96, v[100:101], off
	global_store_dword v[82:83], v96, off
	v_or_b32_e32 v100, v106, v92
	v_lshl_add_u64 v[82:83], v[80:81], 0, v[2:3]
	v_lshlrev_b32_e32 v2, 2, v100
	v_lshl_add_u64 v[100:101], v[0:1], 0, v[2:3]
	s_waitcnt vmcnt(1)
	v_fma_f32 v96, v86, v96, v97
	global_load_dword v100, v[100:101], off
	global_store_dword v[82:83], v96, off
	v_or_b32_e32 v96, v107, v92
	v_lshl_add_u64 v[82:83], v[80:81], 0, v[2:3]
	v_lshlrev_b32_e32 v2, 2, v96
	v_lshl_add_u64 v[96:97], v[0:1], 0, v[2:3]
	s_waitcnt vmcnt(1)
	v_fma_f32 v98, v86, v100, v98
	global_load_dword v98, v[96:97], off
	global_store_dword v[82:83], v98, off
	v_or_b32_e32 v96, v104, v94
	v_lshl_add_u64 v[82:83], v[80:81], 0, v[2:3]
	v_lshlrev_b32_e32 v2, 2, v96
	v_lshl_add_u64 v[96:97], v[0:1], 0, v[2:3]
	v_mfma_f32_16x16x32_bf16 v[100:103], v[72:75], v[64:67], 0
	s_waitcnt vmcnt(1)
; __device__ __forceinline__ void ssd_states_item(KP P, int l, int seq, int c, int g, char* smem) {
;     ...
;   } else {
;     const int bs = seq - 2;
;     const float* h0 = P->st_ssm + ((long)(l * 8 + bs) * 32 + h) * 8192;
;     float* dst = P->out + O_SSMS + ((long)(l * 8 + bs) * 32 + h) * 8192;
;     const float bd = __expf(tot);
; #pragma unroll
;     for (int mb = 0; mb < 4; ++mb)
; #pragma unroll
;       for (int nb = 0; nb < 8; ++nb)
; #pragma unroll
;         for (int j = 0; j < 4; ++j) {
;           const int o = (mb * 16 + (lane >> 4) * 4 + j) * 128 + nb * 16 + (lane & 15);
;           dst[o] = h0[o] * bd + acc[mb][nb][j];
;         }
	v_fmac_f32_e32 v99, v86, v98
	global_load_dword v108, v[96:97], off
	global_store_dword v[82:83], v99, off
	v_mfma_f32_16x16x32_bf16 v[96:99], v[76:79], v[60:63], v[100:103]
	v_lshl_add_u64 v[82:83], v[80:81], 0, v[2:3]
	v_lshlrev_b32_e32 v2, 2, v109
	v_or_b32_e32 v109, v105, v93
	v_lshl_add_u64 v[100:101], v[0:1], 0, v[2:3]
	s_waitcnt vmcnt(1)
	s_nop 2
	v_fma_f32 v96, v86, v108, v96
	global_load_dword v96, v[100:101], off
	global_store_dword v[82:83], v96, off
	v_or_b32_e32 v100, v106, v94
	v_lshl_add_u64 v[82:83], v[80:81], 0, v[2:3]
	v_lshlrev_b32_e32 v2, 2, v100
	v_lshl_add_u64 v[100:101], v[0:1], 0, v[2:3]
	s_waitcnt vmcnt(1)
	v_fma_f32 v96, v86, v96, v97
	global_load_dword v100, v[100:101], off
	global_store_dword v[82:83], v96, off
	v_or_b32_e32 v96, v107, v94
	v_lshl_add_u64 v[82:83], v[80:81], 0, v[2:3]
	v_lshlrev_b32_e32 v2, 2, v96
	v_lshl_add_u64 v[96:97], v[0:1], 0, v[2:3]
	s_waitcnt vmcnt(1)
	v_fma_f32 v98, v86, v100, v98
	global_load_dword v98, v[96:97], off
	global_store_dword v[82:83], v98, off
	v_or_b32_e32 v96, v104, v93
	v_lshl_add_u64 v[82:83], v[80:81], 0, v[2:3]
	v_lshlrev_b32_e32 v2, 2, v96
	v_lshl_add_u64 v[96:97], v[0:1], 0, v[2:3]
	v_mfma_f32_16x16x32_bf16 v[100:103], v[72:75], v[56:59], 0
	s_waitcnt vmcnt(1)
	v_fmac_f32_e32 v99, v86, v98
	global_load_dword v108, v[96:97], off
	global_store_dword v[82:83], v99, off
	v_mfma_f32_16x16x32_bf16 v[96:99], v[76:79], v[48:51], v[100:103]
	v_lshl_add_u64 v[82:83], v[80:81], 0, v[2:3]
	v_lshlrev_b32_e32 v2, 2, v109
	v_or_b32_e32 v109, v105, v90
	v_lshl_add_u64 v[100:101], v[0:1], 0, v[2:3]
	s_waitcnt vmcnt(1)
	s_nop 2
	v_fma_f32 v96, v86, v108, v96
	global_load_dword v96, v[100:101], off
	global_store_dword v[82:83], v96, off
	v_or_b32_e32 v100, v106, v93
	v_lshl_add_u64 v[82:83], v[80:81], 0, v[2:3]
	v_lshlrev_b32_e32 v2, 2, v100
	v_lshl_add_u64 v[100:101], v[0:1], 0, v[2:3]
	s_waitcnt vmcnt(1)
	v_fma_f32 v96, v86, v96, v97
	global_load_dword v100, v[100:101], off
	global_store_dword v[82:83], v96, off
	v_or_b32_e32 v96, v107, v93
	v_lshl_add_u64 v[82:83], v[80:81], 0, v[2:3]
	v_lshlrev_b32_e32 v2, 2, v96
	v_lshl_add_u64 v[96:97], v[0:1], 0, v[2:3]
	s_waitcnt vmcnt(1)
	v_fma_f32 v98, v86, v100, v98
	global_load_dword v98, v[96:97], off
	global_store_dword v[82:83], v98, off
	v_or_b32_e32 v96, v104, v90
	v_lshl_add_u64 v[82:83], v[80:81], 0, v[2:3]
	v_lshlrev_b32_e32 v2, 2, v96
	v_lshl_add_u64 v[96:97], v[0:1], 0, v[2:3]
	v_mfma_f32_16x16x32_bf16 v[100:103], v[72:75], v[36:39], 0
	s_waitcnt vmcnt(1)
	v_fmac_f32_e32 v99, v86, v98
	global_load_dword v108, v[96:97], off
	global_store_dword v[82:83], v99, off
	v_mfma_f32_16x16x32_bf16 v[96:99], v[76:79], v[28:31], v[100:103]
	v_lshl_add_u64 v[82:83], v[80:81], 0, v[2:3]
	v_lshlrev_b32_e32 v2, 2, v109
	v_or_b32_e32 v109, v105, v89
	v_lshl_add_u64 v[100:101], v[0:1], 0, v[2:3]
	s_waitcnt vmcnt(1)
	s_nop 2
	v_fma_f32 v96, v86, v108, v96
	global_load_dword v96, v[100:101], off
	global_store_dword v[82:83], v96, off
	v_or_b32_e32 v100, v106, v90
	v_lshl_add_u64 v[82:83], v[80:81], 0, v[2:3]
	v_lshlrev_b32_e32 v2, 2, v100
	v_lshl_add_u64 v[100:101], v[0:1], 0, v[2:3]
	s_waitcnt vmcnt(1)
	v_fma_f32 v96, v86, v96, v97
	global_load_dword v100, v[100:101], off
	global_store_dword v[82:83], v96, off
	v_or_b32_e32 v96, v107, v90
	v_lshl_add_u64 v[82:83], v[80:81], 0, v[2:3]
	v_lshlrev_b32_e32 v2, 2, v96
	v_lshl_add_u64 v[96:97], v[0:1], 0, v[2:3]
	s_waitcnt vmcnt(1)
	v_fma_f32 v98, v86, v100, v98
	global_load_dword v98, v[96:97], off
	global_store_dword v[82:83], v98, off
	v_or_b32_e32 v96, v104, v89
	v_lshl_add_u64 v[82:83], v[80:81], 0, v[2:3]
	v_lshlrev_b32_e32 v2, 2, v96
	v_lshl_add_u64 v[96:97], v[0:1], 0, v[2:3]
	v_mfma_f32_16x16x32_bf16 v[100:103], v[72:75], v[24:27], 0
	s_waitcnt vmcnt(1)
	v_fmac_f32_e32 v99, v86, v98
	global_load_dword v108, v[96:97], off
	global_store_dword v[82:83], v99, off
	v_mfma_f32_16x16x32_bf16 v[96:99], v[76:79], v[20:23], v[100:103]
	v_lshl_add_u64 v[82:83], v[80:81], 0, v[2:3]
	v_lshlrev_b32_e32 v2, 2, v109
	v_or_b32_e32 v109, 0x1100, v87
	v_lshl_add_u64 v[100:101], v[0:1], 0, v[2:3]
	v_mfma_f32_16x16x32_bf16 v[72:75], v[72:75], v[16:19], 0
	s_waitcnt vmcnt(1)
	s_nop 1
	v_fma_f32 v96, v86, v108, v96
	global_load_dword v96, v[100:101], off
	global_store_dword v[82:83], v96, off
	v_or_b32_e32 v100, v106, v89
	v_lshl_add_u64 v[82:83], v[80:81], 0, v[2:3]
	v_lshlrev_b32_e32 v2, 2, v100
	v_lshl_add_u64 v[100:101], v[0:1], 0, v[2:3]
	v_mfma_f32_16x16x32_bf16 v[72:75], v[76:79], v[12:15], v[72:75]
	v_or_b32_e32 v108, 0x1080, v87
	s_waitcnt vmcnt(1)
	v_fma_f32 v96, v86, v96, v97
	global_load_dword v100, v[100:101], off
	global_store_dword v[82:83], v96, off
	v_or_b32_e32 v96, v107, v89
	v_lshl_add_u64 v[82:83], v[80:81], 0, v[2:3]
	v_lshlrev_b32_e32 v2, 2, v96
	v_lshl_add_u64 v[96:97], v[0:1], 0, v[2:3]
	s_waitcnt vmcnt(1)
	v_fma_f32 v98, v86, v100, v98
	global_load_dword v98, v[96:97], off
	global_store_dword v[82:83], v98, off
	v_or_b32_e32 v96, v104, v88
	v_lshl_add_u64 v[82:83], v[80:81], 0, v[2:3]
	v_lshlrev_b32_e32 v2, 2, v96
	v_lshl_add_u64 v[96:97], v[0:1], 0, v[2:3]
	v_lshl_add_u64 v[76:77], v[80:81], 0, v[2:3]
	s_waitcnt vmcnt(1)
	v_fmac_f32_e32 v99, v86, v98
	global_store_dword v[82:83], v99, off
	global_load_dword v82, v[96:97], off
	v_or_b32_e32 v83, v105, v88
	v_lshlrev_b32_e32 v2, 2, v83
	v_lshl_add_u64 v[78:79], v[0:1], 0, v[2:3]
	s_waitcnt vmcnt(0)
	v_fma_f32 v72, v86, v82, v72
	global_load_dword v72, v[78:79], off
	global_store_dword v[76:77], v72, off
	v_or_b32_e32 v78, v106, v88
	v_lshl_add_u64 v[76:77], v[80:81], 0, v[2:3]
	v_lshlrev_b32_e32 v2, 2, v78
	v_lshl_add_u64 v[78:79], v[0:1], 0, v[2:3]
	v_or_b32_e32 v82, v108, v85
	s_waitcnt vmcnt(1)
; __device__ __forceinline__ bf16x8 cat44(s16x4 a, s16x4 b) { return (bf16x8){a[0], a[1], a[2], a[3], b[0], b[1], b[2], b[3]}; }
; __device__ __forceinline__ void ssd_states_item(KP P, int l, int seq, int c, int g, char* smem) {
;     ...
;     for (int nb = 0; nb < 8; ++nb) {
;       const u16* p0 = Bs + (ks * 32 + trr) * 136 + nb * 16 + trc;
;       const bf16x8 bf = cat44(ldtr(p0), ldtr(p0 + 4 * 136));
; #pragma unroll
;       for (int mb = 0; mb < 4; ++mb) acc[mb][nb] = __builtin_amdgcn_mfma_f32_16x16x32_bf16(af[mb], bf, acc[mb][nb], 0, 0, 0);
;     ...
;     const float bd = __expf(tot);
; #pragma unroll
;     for (int mb = 0; mb < 4; ++mb)
; #pragma unroll
;       for (int nb = 0; nb < 8; ++nb)
; #pragma unroll
;         for (int j = 0; j < 4; ++j) {
;           const int o = (mb * 16 + (lane >> 4) * 4 + j) * 128 + nb * 16 + (lane & 15);
;           dst[o] = h0[o] * bd + acc[mb][nb][j];
	v_fma_f32 v72, v86, v72, v73
	global_load_dword v78, v[78:79], off
	global_store_dword v[76:77], v72, off
	v_or_b32_e32 v76, v107, v88
	v_lshl_add_u64 v[72:73], v[80:81], 0, v[2:3]
	v_lshlrev_b32_e32 v2, 2, v76
	v_lshl_add_u64 v[76:77], v[0:1], 0, v[2:3]
	s_waitcnt vmcnt(1)
	v_fma_f32 v74, v86, v78, v74
	global_store_dword v[72:73], v74, off
	global_load_dword v73, v[76:77], off
	v_or_b32_e32 v72, 0x1000, v87
	v_or_b32_e32 v74, v72, v85
	v_lshl_add_u64 v[76:77], v[80:81], 0, v[2:3]
	v_lshlrev_b32_e32 v2, 2, v74
	v_lshl_add_u64 v[78:79], v[0:1], 0, v[2:3]
	s_waitcnt vmcnt(0)
	v_fmac_f32_e32 v75, v86, v73
	global_load_dword v73, v[78:79], off
	global_store_dword v[76:77], v75, off
	ds_read_b64_tr_b16 v[74:75], v95 offset:17472
	ds_read_b64_tr_b16 v[76:77], v95 offset:18048
	ds_read_b64_tr_b16 v[96:97], v95 offset:22080
	ds_read_b64_tr_b16 v[98:99], v95 offset:22656
	s_waitcnt lgkmcnt(2)
	v_mfma_f32_16x16x32_bf16 v[100:103], v[74:77], v[68:71], 0
	v_lshl_add_u64 v[78:79], v[80:81], 0, v[2:3]
	v_lshlrev_b32_e32 v2, 2, v82
	v_lshl_add_u64 v[82:83], v[0:1], 0, v[2:3]
	s_waitcnt lgkmcnt(0)
	v_mfma_f32_16x16x32_bf16 v[100:103], v[96:99], v[8:11], v[100:103]
	v_mfma_f32_16x16x32_bf16 v[104:107], v[74:77], v[40:43], 0
	s_waitcnt vmcnt(1)
	s_nop 5
	v_fma_f32 v73, v86, v73, v100
	global_load_dword v73, v[82:83], off
	global_store_dword v[78:79], v73, off
	v_or_b32_e32 v82, v109, v85
	v_lshl_add_u64 v[78:79], v[80:81], 0, v[2:3]
	v_lshlrev_b32_e32 v2, 2, v82
	v_lshl_add_u64 v[82:83], v[0:1], 0, v[2:3]
	s_waitcnt vmcnt(1)
	v_fma_f32 v73, v86, v73, v101
	global_load_dword v73, v[82:83], off
	global_store_dword v[78:79], v73, off
	v_or_b32_e32 v82, v110, v85
	v_lshl_add_u64 v[78:79], v[80:81], 0, v[2:3]
	v_lshlrev_b32_e32 v2, 2, v82
	v_lshl_add_u64 v[82:83], v[0:1], 0, v[2:3]
	s_waitcnt vmcnt(1)
	v_fma_f32 v73, v86, v73, v102
	global_load_dword v73, v[82:83], off
	global_store_dword v[78:79], v73, off
	v_or_b32_e32 v82, v72, v91
	v_lshl_add_u64 v[78:79], v[80:81], 0, v[2:3]
	v_lshlrev_b32_e32 v2, 2, v82
	v_lshl_add_u64 v[82:83], v[0:1], 0, v[2:3]
	s_waitcnt vmcnt(1)
	v_fmac_f32_e32 v103, v86, v73
	global_load_dword v73, v[82:83], off
	global_store_dword v[78:79], v103, off
	v_mfma_f32_16x16x32_bf16 v[100:103], v[96:99], v[32:35], v[104:107]
	v_or_b32_e32 v82, v108, v91
	v_lshl_add_u64 v[78:79], v[80:81], 0, v[2:3]
	v_lshlrev_b32_e32 v2, 2, v82
	v_lshl_add_u64 v[82:83], v[0:1], 0, v[2:3]
	v_mfma_f32_16x16x32_bf16 v[104:107], v[74:77], v[52:55], 0
	s_waitcnt vmcnt(1)
	s_nop 1
	v_fma_f32 v73, v86, v73, v100
	global_load_dword v73, v[82:83], off
	global_store_dword v[78:79], v73, off
	v_or_b32_e32 v82, v109, v91
	v_lshl_add_u64 v[78:79], v[80:81], 0, v[2:3]
	v_lshlrev_b32_e32 v2, 2, v82
	v_lshl_add_u64 v[82:83], v[0:1], 0, v[2:3]
	s_waitcnt vmcnt(1)
	v_fma_f32 v73, v86, v73, v101
	global_load_dword v73, v[82:83], off
	global_store_dword v[78:79], v73, off
	v_or_b32_e32 v82, v110, v91
	v_lshl_add_u64 v[78:79], v[80:81], 0, v[2:3]
	v_lshlrev_b32_e32 v2, 2, v82
	v_lshl_add_u64 v[82:83], v[0:1], 0, v[2:3]
	s_waitcnt vmcnt(1)
	v_fma_f32 v73, v86, v73, v102
	global_load_dword v73, v[82:83], off
	global_store_dword v[78:79], v73, off
	v_or_b32_e32 v82, v72, v92
	v_lshl_add_u64 v[78:79], v[80:81], 0, v[2:3]
	v_lshlrev_b32_e32 v2, 2, v82
	v_lshl_add_u64 v[82:83], v[0:1], 0, v[2:3]
	s_waitcnt vmcnt(1)
	v_fmac_f32_e32 v103, v86, v73
	global_load_dword v73, v[82:83], off
	global_store_dword v[78:79], v103, off
	v_mfma_f32_16x16x32_bf16 v[100:103], v[96:99], v[44:47], v[104:107]
	v_or_b32_e32 v82, v108, v92
	v_lshl_add_u64 v[78:79], v[80:81], 0, v[2:3]
	v_lshlrev_b32_e32 v2, 2, v82
	v_lshl_add_u64 v[82:83], v[0:1], 0, v[2:3]
	v_mfma_f32_16x16x32_bf16 v[104:107], v[74:77], v[64:67], 0
	s_waitcnt vmcnt(1)
	s_nop 1
	v_fma_f32 v73, v86, v73, v100
	global_load_dword v73, v[82:83], off
	global_store_dword v[78:79], v73, off
	v_or_b32_e32 v82, v109, v92
	v_lshl_add_u64 v[78:79], v[80:81], 0, v[2:3]
	v_lshlrev_b32_e32 v2, 2, v82
	v_lshl_add_u64 v[82:83], v[0:1], 0, v[2:3]
	s_waitcnt vmcnt(1)
	v_fma_f32 v73, v86, v73, v101
	global_load_dword v73, v[82:83], off
	global_store_dword v[78:79], v73, off
	v_or_b32_e32 v82, v110, v92
	v_lshl_add_u64 v[78:79], v[80:81], 0, v[2:3]
	v_lshlrev_b32_e32 v2, 2, v82
	v_lshl_add_u64 v[82:83], v[0:1], 0, v[2:3]
	s_waitcnt vmcnt(1)
	v_fma_f32 v73, v86, v73, v102
	global_load_dword v73, v[82:83], off
	global_store_dword v[78:79], v73, off
	v_or_b32_e32 v82, v72, v94
	v_lshl_add_u64 v[78:79], v[80:81], 0, v[2:3]
	v_lshlrev_b32_e32 v2, 2, v82
	v_lshl_add_u64 v[82:83], v[0:1], 0, v[2:3]
	s_waitcnt vmcnt(1)
	v_fmac_f32_e32 v103, v86, v73
	global_load_dword v73, v[82:83], off
	global_store_dword v[78:79], v103, off
	v_mfma_f32_16x16x32_bf16 v[100:103], v[96:99], v[60:63], v[104:107]
	v_or_b32_e32 v82, v108, v94
	v_lshl_add_u64 v[78:79], v[80:81], 0, v[2:3]
	v_lshlrev_b32_e32 v2, 2, v82
	v_lshl_add_u64 v[82:83], v[0:1], 0, v[2:3]
	v_mfma_f32_16x16x32_bf16 v[104:107], v[74:77], v[56:59], 0
	s_waitcnt vmcnt(1)
	s_nop 1
	v_fma_f32 v73, v86, v73, v100
	global_load_dword v73, v[82:83], off
	global_store_dword v[78:79], v73, off
	v_or_b32_e32 v82, v109, v94
	v_lshl_add_u64 v[78:79], v[80:81], 0, v[2:3]
	v_lshlrev_b32_e32 v2, 2, v82
	v_lshl_add_u64 v[82:83], v[0:1], 0, v[2:3]
	s_waitcnt vmcnt(1)
	v_fma_f32 v73, v86, v73, v101
	global_load_dword v73, v[82:83], off
	global_store_dword v[78:79], v73, off
	v_or_b32_e32 v82, v110, v94
	v_lshl_add_u64 v[78:79], v[80:81], 0, v[2:3]
	v_lshlrev_b32_e32 v2, 2, v82
	v_lshl_add_u64 v[82:83], v[0:1], 0, v[2:3]
	s_waitcnt vmcnt(1)
; __device__ __forceinline__ bf16x8 cat44(s16x4 a, s16x4 b) { return (bf16x8){a[0], a[1], a[2], a[3], b[0], b[1], b[2], b[3]}; }
; __device__ __forceinline__ void ssd_states_item(KP P, int l, int seq, int c, int g, char* smem) {
;     ...
;     for (int nb = 0; nb < 8; ++nb) {
;       const u16* p0 = Bs + (ks * 32 + trr) * 136 + nb * 16 + trc;
;       const bf16x8 bf = cat44(ldtr(p0), ldtr(p0 + 4 * 136));
; #pragma unroll
;       for (int mb = 0; mb < 4; ++mb) acc[mb][nb] = __builtin_amdgcn_mfma_f32_16x16x32_bf16(af[mb], bf, acc[mb][nb], 0, 0, 0);
;     ...
;     const float bd = __expf(tot);
; #pragma unroll
;     for (int mb = 0; mb < 4; ++mb)
; #pragma unroll
;       for (int nb = 0; nb < 8; ++nb)
; #pragma unroll
;         for (int j = 0; j < 4; ++j) {
;           const int o = (mb * 16 + (lane >> 4) * 4 + j) * 128 + nb * 16 + (lane & 15);
;           dst[o] = h0[o] * bd + acc[mb][nb][j];
	v_fma_f32 v73, v86, v73, v102
	global_load_dword v73, v[82:83], off
	global_store_dword v[78:79], v73, off
	v_or_b32_e32 v82, v72, v93
	v_lshl_add_u64 v[78:79], v[80:81], 0, v[2:3]
	v_lshlrev_b32_e32 v2, 2, v82
	v_lshl_add_u64 v[82:83], v[0:1], 0, v[2:3]
	s_waitcnt vmcnt(1)
	v_fmac_f32_e32 v103, v86, v73
	global_load_dword v73, v[82:83], off
	global_store_dword v[78:79], v103, off
	v_mfma_f32_16x16x32_bf16 v[100:103], v[96:99], v[48:51], v[104:107]
	v_or_b32_e32 v82, v108, v93
	v_lshl_add_u64 v[78:79], v[80:81], 0, v[2:3]
	v_lshlrev_b32_e32 v2, 2, v82
	v_lshl_add_u64 v[82:83], v[0:1], 0, v[2:3]
	v_mfma_f32_16x16x32_bf16 v[104:107], v[74:77], v[36:39], 0
	s_waitcnt vmcnt(1)
	s_nop 1
	v_fma_f32 v73, v86, v73, v100
	global_load_dword v73, v[82:83], off
	global_store_dword v[78:79], v73, off
	v_or_b32_e32 v82, v109, v93
	v_lshl_add_u64 v[78:79], v[80:81], 0, v[2:3]
	v_lshlrev_b32_e32 v2, 2, v82
	v_lshl_add_u64 v[82:83], v[0:1], 0, v[2:3]
	s_waitcnt vmcnt(1)
	v_fma_f32 v73, v86, v73, v101
	global_load_dword v73, v[82:83], off
	global_store_dword v[78:79], v73, off
	v_or_b32_e32 v82, v110, v93
	v_lshl_add_u64 v[78:79], v[80:81], 0, v[2:3]
	v_lshlrev_b32_e32 v2, 2, v82
	v_lshl_add_u64 v[82:83], v[0:1], 0, v[2:3]
	s_waitcnt vmcnt(1)
	v_fma_f32 v73, v86, v73, v102
	global_load_dword v73, v[82:83], off
	global_store_dword v[78:79], v73, off
	v_or_b32_e32 v82, v72, v90
	v_lshl_add_u64 v[78:79], v[80:81], 0, v[2:3]
	v_lshlrev_b32_e32 v2, 2, v82
	v_lshl_add_u64 v[82:83], v[0:1], 0, v[2:3]
	s_waitcnt vmcnt(1)
	v_fmac_f32_e32 v103, v86, v73
	global_load_dword v73, v[82:83], off
	global_store_dword v[78:79], v103, off
	v_mfma_f32_16x16x32_bf16 v[100:103], v[96:99], v[28:31], v[104:107]
	v_or_b32_e32 v82, v108, v90
	v_lshl_add_u64 v[78:79], v[80:81], 0, v[2:3]
	v_lshlrev_b32_e32 v2, 2, v82
	v_lshl_add_u64 v[82:83], v[0:1], 0, v[2:3]
	v_mfma_f32_16x16x32_bf16 v[104:107], v[74:77], v[24:27], 0
	s_waitcnt vmcnt(1)
	s_nop 1
	v_fma_f32 v73, v86, v73, v100
	global_load_dword v73, v[82:83], off
	global_store_dword v[78:79], v73, off
	v_or_b32_e32 v82, v109, v90
	v_lshl_add_u64 v[78:79], v[80:81], 0, v[2:3]
	v_lshlrev_b32_e32 v2, 2, v82
	v_lshl_add_u64 v[82:83], v[0:1], 0, v[2:3]
	s_waitcnt vmcnt(1)
	v_fma_f32 v73, v86, v73, v101
	global_load_dword v73, v[82:83], off
	global_store_dword v[78:79], v73, off
	v_or_b32_e32 v82, v110, v90
	v_lshl_add_u64 v[78:79], v[80:81], 0, v[2:3]
	v_lshlrev_b32_e32 v2, 2, v82
	v_lshl_add_u64 v[82:83], v[0:1], 0, v[2:3]
	s_waitcnt vmcnt(1)
	v_fma_f32 v73, v86, v73, v102
	global_load_dword v73, v[82:83], off
	global_store_dword v[78:79], v73, off
	v_or_b32_e32 v82, v72, v89
	v_lshl_add_u64 v[78:79], v[80:81], 0, v[2:3]
	v_lshlrev_b32_e32 v2, 2, v82
	v_lshl_add_u64 v[82:83], v[0:1], 0, v[2:3]
	s_waitcnt vmcnt(1)
	v_fmac_f32_e32 v103, v86, v73
	global_load_dword v73, v[82:83], off
	global_store_dword v[78:79], v103, off
	v_mfma_f32_16x16x32_bf16 v[100:103], v[96:99], v[20:23], v[104:107]
	v_or_b32_e32 v82, v108, v89
	v_lshl_add_u64 v[78:79], v[80:81], 0, v[2:3]
	v_lshlrev_b32_e32 v2, 2, v82
	v_lshl_add_u64 v[82:83], v[0:1], 0, v[2:3]
	s_waitcnt vmcnt(1)
	s_nop 2
	v_fma_f32 v73, v86, v73, v100
	global_load_dword v73, v[82:83], off
	global_store_dword v[78:79], v73, off
	v_or_b32_e32 v82, v109, v89
	v_lshl_add_u64 v[78:79], v[80:81], 0, v[2:3]
	v_lshlrev_b32_e32 v2, 2, v82
	v_lshl_add_u64 v[82:83], v[0:1], 0, v[2:3]
	s_waitcnt vmcnt(1)
	v_fma_f32 v73, v86, v73, v101
	global_load_dword v73, v[82:83], off
	global_store_dword v[78:79], v73, off
	v_or_b32_e32 v82, v110, v89
	v_lshl_add_u64 v[78:79], v[80:81], 0, v[2:3]
	v_lshlrev_b32_e32 v2, 2, v82
	v_lshl_add_u64 v[82:83], v[0:1], 0, v[2:3]
	s_waitcnt vmcnt(1)
	v_fma_f32 v73, v86, v73, v102
	global_load_dword v82, v[82:83], off
	global_store_dword v[78:79], v73, off
	v_or_b32_e32 v78, v72, v88
	v_mfma_f32_16x16x32_bf16 v[72:75], v[74:77], v[16:19], 0
	v_lshl_add_u64 v[76:77], v[80:81], 0, v[2:3]
	v_lshlrev_b32_e32 v2, 2, v78
	v_lshl_add_u64 v[78:79], v[0:1], 0, v[2:3]
	v_mfma_f32_16x16x32_bf16 v[72:75], v[96:99], v[12:15], v[72:75]
	s_waitcnt vmcnt(1)
	v_fmac_f32_e32 v103, v86, v82
	global_load_dword v82, v[78:79], off
	global_store_dword v[76:77], v103, off
	v_or_b32_e32 v78, v108, v88
	v_lshl_add_u64 v[76:77], v[80:81], 0, v[2:3]
	v_lshlrev_b32_e32 v2, 2, v78
	v_lshl_add_u64 v[78:79], v[0:1], 0, v[2:3]
	s_waitcnt vmcnt(1)
	v_fma_f32 v72, v86, v82, v72
	global_load_dword v72, v[78:79], off
	global_store_dword v[76:77], v72, off
	v_or_b32_e32 v78, v109, v88
	v_lshl_add_u64 v[76:77], v[80:81], 0, v[2:3]
	v_lshlrev_b32_e32 v2, 2, v78
	v_lshl_add_u64 v[78:79], v[0:1], 0, v[2:3]
	v_or_b32_e32 v82, 0x1800, v87
	s_waitcnt vmcnt(1)
	v_fma_f32 v72, v86, v72, v73
	global_load_dword v78, v[78:79], off
	global_store_dword v[76:77], v72, off
	v_or_b32_e32 v76, v110, v88
	v_lshl_add_u64 v[72:73], v[80:81], 0, v[2:3]
	v_lshlrev_b32_e32 v2, 2, v76
	v_lshl_add_u64 v[76:77], v[0:1], 0, v[2:3]
	s_waitcnt vmcnt(1)
	v_fma_f32 v74, v86, v78, v74
	global_load_dword v74, v[76:77], off
	global_store_dword v[72:73], v74, off
	v_or_b32_e32 v76, v82, v85
	v_lshl_add_u64 v[72:73], v[80:81], 0, v[2:3]
	v_lshlrev_b32_e32 v2, 2, v76
	v_lshl_add_u64 v[76:77], v[0:1], 0, v[2:3]
	s_waitcnt vmcnt(1)
	v_fmac_f32_e32 v75, v86, v74
	global_load_dword v83, v[76:77], off
	global_store_dword v[72:73], v75, off
	ds_read_b64_tr_b16 v[72:73], v95 offset:17504
	ds_read_b64_tr_b16 v[74:75], v95 offset:18080
	ds_read_b64_tr_b16 v[76:77], v95 offset:22112
	ds_read_b64_tr_b16 v[78:79], v95 offset:22688
	s_waitcnt lgkmcnt(2)
	v_mfma_f32_16x16x32_bf16 v[68:71], v[72:75], v[68:71], 0
	v_or_b32_e32 v95, 0x1880, v87
	v_or_b32_e32 v96, v95, v85
	s_waitcnt lgkmcnt(0)
; __device__ __forceinline__ bf16x8 cat44(s16x4 a, s16x4 b) { return (bf16x8){a[0], a[1], a[2], a[3], b[0], b[1], b[2], b[3]}; }
; __device__ __forceinline__ void ssd_states_item(KP P, int l, int seq, int c, int g, char* smem) {
;     ...
;     for (int nb = 0; nb < 8; ++nb) {
;       const u16* p0 = Bs + (ks * 32 + trr) * 136 + nb * 16 + trc;
;       const bf16x8 bf = cat44(ldtr(p0), ldtr(p0 + 4 * 136));
; #pragma unroll
;       for (int mb = 0; mb < 4; ++mb) acc[mb][nb] = __builtin_amdgcn_mfma_f32_16x16x32_bf16(af[mb], bf, acc[mb][nb], 0, 0, 0);
;     ...
;     const float bd = __expf(tot);
; #pragma unroll
;     for (int mb = 0; mb < 4; ++mb)
; #pragma unroll
;       for (int nb = 0; nb < 8; ++nb)
; #pragma unroll
;         for (int j = 0; j < 4; ++j) {
;           const int o = (mb * 16 + (lane >> 4) * 4 + j) * 128 + nb * 16 + (lane & 15);
;           dst[o] = h0[o] * bd + acc[mb][nb][j];
	v_mfma_f32_16x16x32_bf16 v[8:11], v[76:79], v[8:11], v[68:71]
	s_nop 3
	v_lshl_add_u64 v[68:69], v[80:81], 0, v[2:3]
	v_lshlrev_b32_e32 v2, 2, v96
	v_lshl_add_u64 v[70:71], v[0:1], 0, v[2:3]
	v_mfma_f32_16x16x32_bf16 v[40:43], v[72:75], v[40:43], 0
	s_waitcnt vmcnt(1)
	v_fma_f32 v8, v86, v83, v8
	global_load_dword v8, v[70:71], off
	global_store_dword v[68:69], v8, off
	v_or_b32_e32 v83, 0x1900, v87
	v_or_b32_e32 v70, v83, v85
	v_lshl_add_u64 v[68:69], v[80:81], 0, v[2:3]
	v_lshlrev_b32_e32 v2, 2, v70
	v_lshl_add_u64 v[70:71], v[0:1], 0, v[2:3]
	v_mfma_f32_16x16x32_bf16 v[24:27], v[72:75], v[24:27], 0
	s_waitcnt vmcnt(1)
	v_fma_f32 v8, v86, v8, v9
	global_load_dword v70, v[70:71], off
	global_store_dword v[68:69], v8, off
	v_or_b32_e32 v71, 0x1980, v87
	v_or_b32_e32 v68, v71, v85
	v_lshl_add_u64 v[8:9], v[80:81], 0, v[2:3]
	v_lshlrev_b32_e32 v2, 2, v68
	v_lshl_add_u64 v[68:69], v[0:1], 0, v[2:3]
	v_mfma_f32_16x16x32_bf16 v[16:19], v[72:75], v[16:19], 0
	s_waitcnt vmcnt(1)
	v_fma_f32 v10, v86, v70, v10
	global_load_dword v10, v[68:69], off
	global_store_dword v[8:9], v10, off
	v_or_b32_e32 v68, v82, v91
	v_lshl_add_u64 v[8:9], v[80:81], 0, v[2:3]
	v_lshlrev_b32_e32 v2, 2, v68
	v_lshl_add_u64 v[68:69], v[0:1], 0, v[2:3]
	s_waitcnt vmcnt(1)
	v_fmac_f32_e32 v11, v86, v10
	global_load_dword v68, v[68:69], off
	global_store_dword v[8:9], v11, off
	v_mfma_f32_16x16x32_bf16 v[8:11], v[76:79], v[32:35], v[40:43]
	v_or_b32_e32 v69, v95, v91
	v_lshl_add_u64 v[32:33], v[80:81], 0, v[2:3]
	v_lshlrev_b32_e32 v2, 2, v69
	v_lshl_add_u64 v[34:35], v[0:1], 0, v[2:3]
	v_or_b32_e32 v40, v82, v92
	s_waitcnt vmcnt(1)
	s_nop 1
	v_fma_f32 v8, v86, v68, v8
	global_load_dword v8, v[34:35], off
	global_store_dword v[32:33], v8, off
	v_or_b32_e32 v34, v83, v91
	v_lshl_add_u64 v[32:33], v[80:81], 0, v[2:3]
	v_lshlrev_b32_e32 v2, 2, v34
	v_lshl_add_u64 v[34:35], v[0:1], 0, v[2:3]
	s_waitcnt vmcnt(1)
	v_fma_f32 v8, v86, v8, v9
	global_load_dword v34, v[34:35], off
	global_store_dword v[32:33], v8, off
	v_or_b32_e32 v32, v71, v91
	v_lshl_add_u64 v[8:9], v[80:81], 0, v[2:3]
	v_lshlrev_b32_e32 v2, 2, v32
	v_lshl_add_u64 v[32:33], v[0:1], 0, v[2:3]
	s_waitcnt vmcnt(1)
	v_fma_f32 v10, v86, v34, v10
	global_load_dword v10, v[32:33], off
	global_store_dword v[8:9], v10, off
	v_lshl_add_u64 v[8:9], v[80:81], 0, v[2:3]
	v_lshlrev_b32_e32 v2, 2, v40
	v_lshl_add_u64 v[40:41], v[0:1], 0, v[2:3]
	v_mfma_f32_16x16x32_bf16 v[32:35], v[72:75], v[52:55], 0
	v_mov_b32_e32 v52, 0
	s_waitcnt vmcnt(1)
	v_fmac_f32_e32 v11, v86, v10
	global_load_dword v40, v[40:41], off
	global_store_dword v[8:9], v11, off
	v_mfma_f32_16x16x32_bf16 v[8:11], v[76:79], v[44:47], v[32:35]
	v_or_b32_e32 v41, v95, v92
	s_nop 1
	v_lshl_add_u64 v[32:33], v[80:81], 0, v[2:3]
	v_lshlrev_b32_e32 v2, 2, v41
	v_lshl_add_u64 v[34:35], v[0:1], 0, v[2:3]
	s_waitcnt vmcnt(1)
	s_nop 0
	v_fma_f32 v8, v86, v40, v8
	global_load_dword v8, v[34:35], off
	global_store_dword v[32:33], v8, off
	v_or_b32_e32 v34, v83, v92
	v_lshl_add_u64 v[32:33], v[80:81], 0, v[2:3]
	v_lshlrev_b32_e32 v2, 2, v34
	v_lshl_add_u64 v[34:35], v[0:1], 0, v[2:3]
	v_or_b32_e32 v40, v82, v94
	s_waitcnt vmcnt(1)
	v_fma_f32 v8, v86, v8, v9
	global_load_dword v34, v[34:35], off
	global_store_dword v[32:33], v8, off
	v_or_b32_e32 v32, v71, v92
	v_lshl_add_u64 v[8:9], v[80:81], 0, v[2:3]
	v_lshlrev_b32_e32 v2, 2, v32
	v_lshl_add_u64 v[32:33], v[0:1], 0, v[2:3]
	s_waitcnt vmcnt(1)
	v_fma_f32 v10, v86, v34, v10
	global_load_dword v10, v[32:33], off
	global_store_dword v[8:9], v10, off
	v_lshl_add_u64 v[8:9], v[80:81], 0, v[2:3]
	v_lshlrev_b32_e32 v2, 2, v40
	v_lshl_add_u64 v[40:41], v[0:1], 0, v[2:3]
	v_mfma_f32_16x16x32_bf16 v[32:35], v[72:75], v[64:67], 0
	s_waitcnt vmcnt(1)
	v_fmac_f32_e32 v11, v86, v10
	global_load_dword v40, v[40:41], off
	global_store_dword v[8:9], v11, off
	v_mfma_f32_16x16x32_bf16 v[8:11], v[76:79], v[60:63], v[32:35]
	v_or_b32_e32 v41, v95, v94
	s_nop 1
	v_lshl_add_u64 v[32:33], v[80:81], 0, v[2:3]
	v_lshlrev_b32_e32 v2, 2, v41
	v_lshl_add_u64 v[34:35], v[0:1], 0, v[2:3]
	s_waitcnt vmcnt(1)
	s_nop 0
	v_fma_f32 v8, v86, v40, v8
	global_load_dword v8, v[34:35], off
	global_store_dword v[32:33], v8, off
	v_or_b32_e32 v34, v83, v94
	v_lshl_add_u64 v[32:33], v[80:81], 0, v[2:3]
	v_lshlrev_b32_e32 v2, 2, v34
	v_lshl_add_u64 v[34:35], v[0:1], 0, v[2:3]
	v_or_b32_e32 v40, v82, v93
	s_waitcnt vmcnt(1)
	v_fma_f32 v8, v86, v8, v9
	global_load_dword v34, v[34:35], off
	global_store_dword v[32:33], v8, off
	v_or_b32_e32 v32, v71, v94
	v_lshl_add_u64 v[8:9], v[80:81], 0, v[2:3]
	v_lshlrev_b32_e32 v2, 2, v32
	v_lshl_add_u64 v[32:33], v[0:1], 0, v[2:3]
	s_waitcnt vmcnt(1)
	v_fma_f32 v10, v86, v34, v10
	global_load_dword v10, v[32:33], off
	global_store_dword v[8:9], v10, off
	v_lshl_add_u64 v[8:9], v[80:81], 0, v[2:3]
	v_lshlrev_b32_e32 v2, 2, v40
	v_lshl_add_u64 v[40:41], v[0:1], 0, v[2:3]
	v_mfma_f32_16x16x32_bf16 v[32:35], v[72:75], v[56:59], 0
	s_waitcnt vmcnt(1)
	v_fmac_f32_e32 v11, v86, v10
	global_load_dword v40, v[40:41], off
	global_store_dword v[8:9], v11, off
	v_mfma_f32_16x16x32_bf16 v[8:11], v[76:79], v[48:51], v[32:35]
	v_or_b32_e32 v41, v95, v93
	s_nop 1
	v_lshl_add_u64 v[32:33], v[80:81], 0, v[2:3]
	v_lshlrev_b32_e32 v2, 2, v41
	v_lshl_add_u64 v[34:35], v[0:1], 0, v[2:3]
	s_waitcnt vmcnt(1)
; __device__ __forceinline__ void ssd_states_item(KP P, int l, int seq, int c, int g, char* smem) {
;     ...
;     const float bd = __expf(tot);
; #pragma unroll
;     for (int mb = 0; mb < 4; ++mb)
; #pragma unroll
;       for (int nb = 0; nb < 8; ++nb)
; #pragma unroll
;         for (int j = 0; j < 4; ++j) {
;           const int o = (mb * 16 + (lane >> 4) * 4 + j) * 128 + nb * 16 + (lane & 15);
;           dst[o] = h0[o] * bd + acc[mb][nb][j];
;         }
;   }
;   __syncthreads();
; __device__ __forceinline__ void ssd_out_item(KP P, int l, int seq, int c, int g, char* smem) {
;     ...
;   const float a = -__expf(P->a_log[l * 32 + h]);
;   float dt, acum;
;   ssd_dt_acum(DT, rb, L, h, a, lane, dt, acum);
	s_nop 0
	v_fma_f32 v8, v86, v40, v8
	global_load_dword v8, v[34:35], off
	global_store_dword v[32:33], v8, off
	v_or_b32_e32 v34, v83, v93
	v_lshl_add_u64 v[32:33], v[80:81], 0, v[2:3]
	v_lshlrev_b32_e32 v2, 2, v34
	v_lshl_add_u64 v[34:35], v[0:1], 0, v[2:3]
	v_or_b32_e32 v40, v82, v90
	s_waitcnt vmcnt(1)
	v_fma_f32 v8, v86, v8, v9
	global_load_dword v34, v[34:35], off
	global_store_dword v[32:33], v8, off
	v_or_b32_e32 v32, v71, v93
	v_lshl_add_u64 v[8:9], v[80:81], 0, v[2:3]
	v_lshlrev_b32_e32 v2, 2, v32
	v_lshl_add_u64 v[32:33], v[0:1], 0, v[2:3]
	s_waitcnt vmcnt(1)
	v_fma_f32 v10, v86, v34, v10
	global_load_dword v10, v[32:33], off
	global_store_dword v[8:9], v10, off
	v_lshl_add_u64 v[8:9], v[80:81], 0, v[2:3]
	v_lshlrev_b32_e32 v2, 2, v40
	v_mfma_f32_16x16x32_bf16 v[32:35], v[72:75], v[36:39], 0
	v_lshl_add_u64 v[36:37], v[0:1], 0, v[2:3]
	s_waitcnt vmcnt(1)
	v_fmac_f32_e32 v11, v86, v10
	global_load_dword v36, v[36:37], off
	global_store_dword v[8:9], v11, off
	v_mfma_f32_16x16x32_bf16 v[8:11], v[76:79], v[28:31], v[32:35]
	v_or_b32_e32 v37, v95, v90
	v_lshl_add_u64 v[28:29], v[80:81], 0, v[2:3]
	v_lshlrev_b32_e32 v2, 2, v37
	v_lshl_add_u64 v[30:31], v[0:1], 0, v[2:3]
	s_waitcnt vmcnt(1)
	s_nop 2
	v_fma_f32 v8, v86, v36, v8
	global_load_dword v8, v[30:31], off
	global_store_dword v[28:29], v8, off
	v_or_b32_e32 v30, v83, v90
	v_lshl_add_u64 v[28:29], v[80:81], 0, v[2:3]
	v_lshlrev_b32_e32 v2, 2, v30
	v_lshl_add_u64 v[30:31], v[0:1], 0, v[2:3]
	s_waitcnt vmcnt(1)
	v_fma_f32 v8, v86, v8, v9
	global_load_dword v30, v[30:31], off
	global_store_dword v[28:29], v8, off
	v_or_b32_e32 v28, v71, v90
	v_lshl_add_u64 v[8:9], v[80:81], 0, v[2:3]
	v_lshlrev_b32_e32 v2, 2, v28
	v_lshl_add_u64 v[28:29], v[0:1], 0, v[2:3]
	s_waitcnt vmcnt(1)
	v_fma_f32 v10, v86, v30, v10
	global_load_dword v10, v[28:29], off
	global_store_dword v[8:9], v10, off
	v_or_b32_e32 v28, v82, v89
	v_lshl_add_u64 v[8:9], v[80:81], 0, v[2:3]
	v_lshlrev_b32_e32 v2, 2, v28
	v_lshl_add_u64 v[28:29], v[0:1], 0, v[2:3]
	s_waitcnt vmcnt(1)
	v_fmac_f32_e32 v11, v86, v10
	global_load_dword v28, v[28:29], off
	global_store_dword v[8:9], v11, off
	v_mfma_f32_16x16x32_bf16 v[8:11], v[76:79], v[20:23], v[24:27]
	v_or_b32_e32 v29, v95, v89
	v_lshl_add_u64 v[20:21], v[80:81], 0, v[2:3]
	v_lshlrev_b32_e32 v2, 2, v29
	v_lshl_add_u64 v[22:23], v[0:1], 0, v[2:3]
	s_waitcnt vmcnt(1)
	s_nop 2
	v_fma_f32 v8, v86, v28, v8
	global_load_dword v8, v[22:23], off
	global_store_dword v[20:21], v8, off
	v_or_b32_e32 v22, v83, v89
	v_lshl_add_u64 v[20:21], v[80:81], 0, v[2:3]
	v_lshlrev_b32_e32 v2, 2, v22
	v_lshl_add_u64 v[22:23], v[0:1], 0, v[2:3]
	s_waitcnt vmcnt(1)
	v_fma_f32 v8, v86, v8, v9
	global_load_dword v22, v[22:23], off
	global_store_dword v[20:21], v8, off
	v_or_b32_e32 v20, v71, v89
	v_lshl_add_u64 v[8:9], v[80:81], 0, v[2:3]
	v_lshlrev_b32_e32 v2, 2, v20
	v_lshl_add_u64 v[20:21], v[0:1], 0, v[2:3]
	s_waitcnt vmcnt(1)
	v_fma_f32 v10, v86, v22, v10
	global_load_dword v10, v[20:21], off
	global_store_dword v[8:9], v10, off
	v_or_b32_e32 v20, v82, v88
	v_lshl_add_u64 v[8:9], v[80:81], 0, v[2:3]
	v_lshlrev_b32_e32 v2, 2, v20
	v_lshl_add_u64 v[20:21], v[0:1], 0, v[2:3]
	v_mov_b32_e32 v22, v188
	s_waitcnt vmcnt(1)
	v_fmac_f32_e32 v11, v86, v10
	global_load_dword v20, v[20:21], off
	global_store_dword v[8:9], v11, off
	v_mfma_f32_16x16x32_bf16 v[8:11], v[76:79], v[12:15], v[16:19]
	v_or_b32_e32 v21, v95, v88
	v_lshl_add_u64 v[12:13], v[80:81], 0, v[2:3]
	v_lshlrev_b32_e32 v2, 2, v21
	v_lshl_add_u64 v[14:15], v[0:1], 0, v[2:3]
	s_waitcnt vmcnt(1)
	s_nop 2
	v_fma_f32 v8, v86, v20, v8
	global_load_dword v8, v[14:15], off
	global_store_dword v[12:13], v8, off
	v_or_b32_e32 v14, v83, v88
	v_lshl_add_u64 v[12:13], v[80:81], 0, v[2:3]
	v_lshlrev_b32_e32 v2, 2, v14
	v_lshl_add_u64 v[14:15], v[0:1], 0, v[2:3]
	s_waitcnt vmcnt(1)
	v_fma_f32 v8, v86, v8, v9
	global_store_dword v[12:13], v8, off
	global_load_dword v12, v[14:15], off
	v_or_b32_e32 v13, v71, v88
	v_lshl_add_u64 v[8:9], v[80:81], 0, v[2:3]
	v_lshlrev_b32_e32 v2, 2, v13
	v_lshl_add_u64 v[0:1], v[0:1], 0, v[2:3]
	s_waitcnt vmcnt(0)
	v_fma_f32 v10, v86, v12, v10
	global_store_dword v[8:9], v10, off
	global_load_dword v8, v[0:1], off
	v_lshl_add_u64 v[0:1], v[80:81], 0, v[2:3]
	s_waitcnt vmcnt(0)
	v_fmac_f32_e32 v11, v86, v8
	global_store_dword v[0:1], v11, off
	s_barrier
	s_load_dwordx2 s[4:5], s[6:7], 0xd8
	s_load_dwordx2 s[8:9], s[6:7], 0x60
	v_ashrrev_i32_e32 v24, 6, v22
	v_add_u32_e32 v100, s13, v24
	v_add_u32_e32 v104, s44, v100
	v_ashrrev_i32_e32 v105, 31, v104
	s_waitcnt lgkmcnt(0)
	v_lshl_add_u64 v[0:1], v[104:105], 2, s[8:9]
	global_load_dword v0, v[0:1], off
	s_add_u32 s8, s4, s0
	v_and_b32_e32 v23, 63, v22
	s_addc_u32 s9, s5, s1
	v_cmp_gt_u32_e64 s[4:5], 16, v23
	v_ashrrev_i32_e32 v101, 31, v100
	s_and_saveexec_b64 s[0:1], s[4:5]
	s_cbranch_execz .LBB0_566
	v_or_b32_e32 v2, s15, v23
	v_lshlrev_b64 v[8:9], 7, v[2:3]
	v_lshl_add_u64 v[8:9], s[8:9], 0, v[8:9]
	v_lshl_add_u64 v[8:9], v[100:101], 2, v[8:9]
	v_add_co_u32_e32 v8, vcc, 0x34b60000, v8
	s_nop 1
	v_addc_co_u32_e32 v9, vcc, 0, v9, vcc
	global_load_dword v84, v[8:9], off
